# u1 + diff loop DMA block: running 64-bit source addresses (3 adds/step in PV gaps) instead of 6 adds in the inter-segment block, m0 save/restore dropped
# baseline (speedup 1.0000x reference)
; __device__ __forceinline__ float fsub_s(float a,float b){float r;asm("v_sub_f32_e32 %0, %1, %2":"=v"(r):"v"(a),"v"(b));return r;}
; #define WAIT_BAR(N) asm volatile("s_waitcnt vmcnt(" #N ") lgkmcnt(0)\n\ts_barrier":::"memory")
;   #define DMA_K(t,slot) glds16(ksrc+(long)(t)*KVBLK*kp,(unsigned)__builtin_amdgcn_readfirstlane(kdst+(slot)))
;   #define DMA_V(t,slot) glds16(vsrc+(long)(t)*KVBLK*vp,(unsigned)__builtin_amdgcn_readfirstlane(vdst+(slot)))
;   #define ROT() do{sl_prev=sl_cur;sl_cur=sl_next;sl_next=(sl_next==(NSLOT-1)*SLOTB)?0:sl_next+SLOTB;}while(0)
;   #define DMA_K(t,slot) glds16(ksrc+(long)(t)*KVBLK*kp,(unsigned)__builtin_amdgcn_readfirstlane(kdst+(slot)))
;   #define DMA_V(t,slot) glds16(vsrc+(long)(t)*KVBLK*vp,(unsigned)__builtin_amdgcn_readfirstlane(vdst+(slot)))
; template<int THRL,bool NOMAX=false> __device__ __forceinline__ void attn_unit_v128(const bf16*Qu,int qp,const bf16*__restrict__ Kh,int kp,const bf16*__restrict__ Vh,int vp,bf16*Ou,int op,int NT,char*shm,int tid_in){
;     ...
;   const bf16*ksrc=Kh+(long)lane*kp+wid*8;
;   const bf16*vsrc=Vh+(long)(16*(wid&3)+(lane>>2))*vp+(wid>>2)*32+(lane&3)*8;
;   const unsigned kdst=lds0+V2_LDS_K+wid*1024, vdst=lds0+V2_LDS_V+wid*1024;
;     ...
;   const int vb0=(int)(lds0+V2_LDS_V)+((lane>>4)&1)*32+(lane&3)*8+(4*hi+((lane&15)>>2))*64;
;   const char*Kbase=shm+V2_LDS_K; bf16x8 kf[8];
;   const lds_cptr shm3=(lds_cptr)shm; const lds_cptr kp0=shm3+V2_LDS_K+hi*1024+r32*16; const lds_cptr vp0=shm3+V2_LDS_V+((lane>>4)&1)*32+(lane&3)*8+(4*hi+((lane&15)>>2))*64;
;   DMA_K(0,0);DMA_V(0,0);DMA_K(1,SLOTB);
;   bf16x8 qr[4];
;   #pragma unroll
;   for(int d0=0;d0<4;++d0)qr[d0]=*reinterpret_cast<const bf16x8*>(&Qw[(long)r32*qp+d0*16+hi*8]);
;   float mhat=0.f,l_reg=0.f;f32x16 o[4];o[0]=f32x16{};o[1]=f32x16{};o[2]=f32x16{};o[3]=f32x16{};
;   const f32x16 zero16=f32x16{};
;   bool resc=false;
;     ...
;   f32x16 pA0,pA1,pB0,pB1;
;   int sl_prev=0,sl_cur=0,sl_next=SLOTB;
;     ...
;   DMA_K(2,2*SLOTB);
;   WAIT_BAR(3);
;   qkt0(pA0,pA1,Kbase,qr,r32,hi);asm volatile("s_nop 15\n\ts_nop 7":"+v"(pA0),"+v"(pA1));
;   START(pA0,pA1);
;   if constexpr(NOMAX){ _Pragma("unroll") for(int r=0;r<16;++r)pA1[r]=__builtin_amdgcn_exp2f(pA1[r]); } else { _Pragma("unroll") for(int r=0;r<16;++r)pA1[r]=__builtin_amdgcn_exp2f(fsub_s(pA1[r],mhat)); }
;   WAIT_BAR(0);
;   DMA_K(3,0);DMA_V(1,SLOTB);
;   ROT();
;   kload8(kf,kp0+sl_cur);
;   WAIT_BAR(3);
.LBB0_795:
	s_and_b64 vcc, exec, s[6:7]
	s_cbranch_vccz .LBB0_839
	v_readlane_b32 s2, v253, 6
	v_mbcnt_lo_u32_b32 v0, -1, 0
	v_mbcnt_hi_u32_b32 v0, -1, v0
	s_mov_b32 s86, 1
	s_waitcnt vmcnt(7)
	v_or_b32_e32 v46, s2, v0
	s_nop 0
	v_readfirstlane_b32 s39, v46
	s_ashr_i32 s38, s39, 6
	s_lshl_b32 s2, s38, 5
	s_ashr_i32 s3, s2, 31
	s_lshl_b64 s[2:3], s[2:3], 10
	v_and_b32_e32 v206, 63, v46
	s_add_u32 s6, s33, s2
	s_addc_u32 s7, s76, s3
	v_lshrrev_b32_e32 v2, 3, v206
	v_lshl_add_u32 v2, s38, 3, v2
	v_lshrrev_b32_e32 v3, 1, v2
	v_xor_b32_e32 v3, v3, v206
	v_and_b32_e32 v3, 7, v3
	v_lshlrev_b32_e32 v2, 10, v2
	v_lshl_add_u32 v0, v3, 4, v2
	v_lshl_add_u64 v[194:195], s[36:37], 0, v[0:1]
	s_lshl_b32 s8, s38, 4
	v_bfe_u32 v0, v46, 2, 4
	v_and_or_b32 v0, s8, 48, v0
	s_ashr_i32 s8, s39, 3
	s_andn2_b32 s8, s8, 31
	v_lshlrev_b32_e32 v0, 10, v0
	s_ashr_i32 s9, s8, 31
	s_lshl_b32 s33, s38, 10
	v_lshl_add_u64 v[2:3], s[34:35], 0, v[0:1]
	v_lshlrev_b32_e32 v209, 3, v46
	s_cmp_lg_u32 0, -1
	v_lshl_add_u64 v[2:3], s[8:9], 1, v[2:3]
	v_and_b32_e32 v211, 24, v209
	s_cselect_b32 s8, 0, 0
	v_lshlrev_b32_e32 v0, 1, v211
	s_add_i32 s33, s33, s8
	s_mov_b32 s8, m0
	s_mov_b32 m0, s33
	s_nop 0
	global_load_lds_dwordx4 v[194:195], off
	s_mov_b32 m0, s8
	v_and_b32_e32 v207, 31, v46
	v_lshl_add_u64 v[196:197], v[2:3], 0, v[0:1]
	s_add_i32 s34, s33, 0x6000
	s_mov_b32 s8, m0
	s_mov_b32 m0, s34
	s_nop 0
	global_load_lds_dwordx4 v[196:197], off
	s_mov_b32 m0, s8
	v_bfe_u32 v208, v46, 5, 1
	v_lshl_add_u64 v[198:199], v[196:197], 0, s[0:1]
	s_add_i32 s8, s33, 0x8000
	s_mov_b32 s9, m0
	s_mov_b32 m0, s8
	s_nop 0
	global_load_lds_dwordx4 v[198:199], off
	s_mov_b32 m0, s9
	s_mov_b64 s[76:77], 0x10000
	v_lshlrev_b32_e32 v0, 10, v207
	v_lshl_add_u64 v[2:3], v[194:195], 0, s[76:77]
	s_add_i32 s8, s33, 0x2000
	s_mov_b32 s9, m0
	s_mov_b32 m0, s8
	s_nop 0
	global_load_lds_dwordx4 v[2:3], off
	s_mov_b32 m0, s9
	v_lshl_or_b32 v0, v208, 4, v0
	global_load_dwordx4 v[154:157], v0, s[6:7]
	global_load_dwordx4 v[150:153], v0, s[6:7] offset:32
	global_load_dwordx4 v[142:145], v0, s[6:7] offset:64
	global_load_dwordx4 v[134:137], v0, s[6:7] offset:96
	s_mov_b64 s[6:7], 0x20000
	v_lshlrev_b32_e32 v0, 7, v207
	v_bfe_u32 v2, v207, 2, 2
	v_lshl_add_u32 v0, v2, 5, v0
	v_bfe_u32 v2, v207, 1, 1
	v_xor_b32_e32 v2, v2, v208
	v_lshl_add_u32 v212, v2, 4, v0
	v_xor_b32_e32 v217, 32, v212
	v_xor_b32_e32 v218, 64, v212
	v_xor_b32_e32 v219, 0x60, v212
	v_lshl_add_u64 v[2:3], v[194:195], 0, s[6:7]
	s_add_i32 s6, s33, 0x4000
	s_mov_b32 s7, m0
	s_mov_b32 m0, s6
	s_nop 0
	global_load_lds_dwordx4 v[2:3], off
	s_mov_b32 m0, s7
	s_waitcnt vmcnt(3) lgkmcnt(0)
	s_barrier
	ds_read_b128 v[2:5], v212
	ds_read_b128 v[6:9], v212 offset:4096
	ds_read_b128 v[34:37], v217
	ds_read_b128 v[38:41], v217 offset:4096
	s_mov_b64 s[6:7], 0x30000
	v_lshlrev_b32_e32 v0, 1, v46
	v_and_b32_e32 v213, 32, v0
	s_mov_b32 s8, 0
	s_movk_i32 s35, 0x2000
	s_movk_i32 s36, 0x4000
	s_and_b64 vcc, exec, s[4:5]
	s_waitcnt vmcnt(3) lgkmcnt(3)
	v_mfma_f32_32x32x16_bf16 v[18:33], v[2:5], v[154:157], 0
	s_waitcnt lgkmcnt(2)
	v_mfma_f32_32x32x16_bf16 v[2:17], v[6:9], v[154:157], 0
	s_waitcnt vmcnt(2) lgkmcnt(1)
	v_mfma_f32_32x32x16_bf16 v[18:33], v[34:37], v[150:153], v[18:33]
	ds_read_b128 v[34:37], v218 offset:4096
	ds_read_b128 v[42:45], v218
	s_waitcnt lgkmcnt(2)
	v_mfma_f32_32x32x16_bf16 v[2:17], v[38:41], v[150:153], v[2:17]
	s_waitcnt vmcnt(1) lgkmcnt(0)
	v_mfma_f32_32x32x16_bf16 v[18:33], v[42:45], v[142:145], v[18:33]
	ds_read_b128 v[38:41], v219 offset:4096
	ds_read_b128 v[42:45], v219
	v_mfma_f32_32x32x16_bf16 v[2:17], v[34:37], v[142:145], v[2:17]
	v_lshlrev_b32_e32 v34, 4, v46
	v_and_b32_e32 v0, 0xc0, v34
	v_lshl_or_b32 v0, v208, 8, v0
	v_add_u32_e32 v34, 0, v213
	v_add3_u32 v214, v34, v211, v0
	s_waitcnt vmcnt(0) lgkmcnt(0)
	v_mfma_f32_32x32x16_bf16 v[18:33], v[42:45], v[134:137], v[18:33]
	v_mfma_f32_32x32x16_bf16 v[2:17], v[38:41], v[134:137], v[2:17]
	s_nop 15
	s_nop 7
	s_waitcnt vmcnt(0) lgkmcnt(0)
	s_barrier
	s_nop 10
	v_exp_f32_e32 v82, v18
	v_exp_f32_e32 v83, v19
	v_exp_f32_e32 v66, v2
	v_exp_f32_e32 v67, v3
	v_lshl_add_u64 v[2:3], v[194:195], 0, s[6:7]
	s_mov_b32 s6, m0
	s_mov_b32 m0, s33
	s_nop 0
	global_load_lds_dwordx4 v[2:3], off
	s_mov_b32 m0, s6
	v_lshl_add_u64 v[2:3], v[196:197], 0, s[76:77]
	s_add_i32 s6, s33, 0xa000
	s_mov_b32 s7, m0
	s_mov_b32 m0, s6
	s_nop 0
	global_load_lds_dwordx4 v[2:3], off
	s_mov_b32 m0, s7
	s_mov_b64 s[6:7], 0x10080
	v_lshl_add_u64 v[2:3], v[196:197], 0, s[6:7]
	s_add_i32 s6, s33, 0xc000
	s_mov_b32 s7, m0
	s_mov_b32 m0, s6
	s_nop 0
	global_load_lds_dwordx4 v[2:3], off
	s_mov_b32 m0, s7
	ds_read_b128 v[186:189], v212 offset:8192
	ds_read_b128 v[174:177], v212 offset:12288
	ds_read_b128 v[190:193], v217 offset:8192
	ds_read_b128 v[178:181], v217 offset:12288
	ds_read_b128 v[182:185], v218 offset:8192
	ds_read_b128 v[166:169], v218 offset:12288
	ds_read_b128 v[170:173], v219 offset:8192
	ds_read_b128 v[162:165], v219 offset:12288
	v_exp_f32_e32 v84, v20
	v_exp_f32_e32 v85, v21
	v_exp_f32_e32 v86, v22
	v_exp_f32_e32 v87, v23
	v_exp_f32_e32 v88, v24
	v_exp_f32_e32 v89, v25
	v_exp_f32_e32 v90, v26
	v_exp_f32_e32 v91, v27
	v_exp_f32_e32 v92, v28
	v_exp_f32_e32 v93, v29
	v_exp_f32_e32 v94, v30
	v_exp_f32_e32 v95, v31
	v_exp_f32_e32 v96, v32
	v_exp_f32_e32 v97, v33
	v_exp_f32_e32 v68, v4
	v_exp_f32_e32 v69, v5
	v_exp_f32_e32 v70, v6
	v_exp_f32_e32 v71, v7
	v_exp_f32_e32 v72, v8
	v_exp_f32_e32 v73, v9
	v_exp_f32_e32 v74, v10
	v_exp_f32_e32 v75, v11
	v_exp_f32_e32 v76, v12
	v_exp_f32_e32 v77, v13
	v_exp_f32_e32 v78, v14
	v_exp_f32_e32 v79, v15
	v_exp_f32_e32 v80, v16
	v_exp_f32_e32 v81, v17
	s_waitcnt vmcnt(3) lgkmcnt(0)
	s_barrier
; #define WAIT_BAR(N) asm volatile("s_waitcnt vmcnt(" #N ") lgkmcnt(0)\n\ts_barrier":::"memory")
;   #define RESC() do{ if(resc){ asm volatile("s_waitcnt lgkmcnt(0)":::"memory"); \
;       _Pragma("unroll") for(int d_=0;d_<2;++d_) _Pragma("unroll") for(int r=0;r<16;++r)o[d_][r]*=wsf[crow(r,hi)]; } }while(0)
;   #define ROT() do{sl_prev=sl_cur;sl_cur=sl_next;sl_next=(sl_next==(NSLOT-1)*SLOTB)?0:sl_next+SLOTB;}while(0)
;   #define RESC() do{ if(resc){ asm volatile("s_waitcnt lgkmcnt(0)":::"memory"); \
;       _Pragma("unroll") for(int d_=0;d_<4;++d_) _Pragma("unroll") for(int r=0;r<16;++r)o[d_][r]*=wsf[crow(r,hi)]; } }while(0)
;   #define ROT() do{sl_prev=sl_cur;sl_cur=sl_next;sl_next=(sl_next==(NSLOT-1)*SLOTB)?0:sl_next+SLOTB;}while(0)
; template<int THRL,bool NOMAX=false> __device__ __forceinline__ void attn_unit_v128(const bf16*Qu,int qp,const bf16*__restrict__ Kh,int kp,const bf16*__restrict__ Vh,int vp,bf16*Ou,int op,int NT,char*shm,int tid_in){
;     ...
;   int t=1;
;   for(;t+5<NT;t+=2){
;     STEP(pB0,pB1,pA0,pA1,t,true,true,true);     WAIT_BAR(3); RESC(); ROT();
	s_cbranch_vccnz .LBB0_800
	v_mov_b32_e32 v210, 0
	s_mov_b32 s9, 0
	s_mov_b32 s10, 6
	s_mov_b64 s[4:5], 0
	v_mov_b32_e32 v34, 0
	v_mov_b32_e32 v35, v210
	v_mov_b32_e32 v36, v210
	v_mov_b32_e32 v37, v210
	v_mov_b32_e32 v38, v210
	v_mov_b32_e32 v39, v210
	v_mov_b32_e32 v40, v210
	v_mov_b32_e32 v41, v210
	v_mov_b32_e32 v42, v210
	v_mov_b32_e32 v43, v210
	v_mov_b32_e32 v44, v210
	v_mov_b32_e32 v45, v210
	v_mov_b32_e32 v46, v210
	v_mov_b32_e32 v47, v210
	v_mov_b32_e32 v48, v210
	v_mov_b32_e32 v49, v210
	v_mov_b32_e32 v50, 0
	v_mov_b32_e32 v51, v210
	v_mov_b32_e32 v52, v210
	v_mov_b32_e32 v53, v210
	v_mov_b32_e32 v54, v210
	v_mov_b32_e32 v55, v210
	v_mov_b32_e32 v56, v210
	v_mov_b32_e32 v57, v210
	v_mov_b32_e32 v58, v210
	v_mov_b32_e32 v59, v210
	v_mov_b32_e32 v60, v210
	v_mov_b32_e32 v61, v210
	v_mov_b32_e32 v62, v210
	v_mov_b32_e32 v63, v210
	v_mov_b32_e32 v64, v210
	v_mov_b32_e32 v65, v210
	v_mov_b32_e32 v2, 0
	v_mov_b32_e32 v3, v210
	v_mov_b32_e32 v4, v210
	v_mov_b32_e32 v5, v210
	v_mov_b32_e32 v6, v210
	v_mov_b32_e32 v7, v210
	v_mov_b32_e32 v8, v210
	v_mov_b32_e32 v9, v210
	v_mov_b32_e32 v10, v210
	v_mov_b32_e32 v11, v210
	v_mov_b32_e32 v12, v210
	v_mov_b32_e32 v13, v210
	v_mov_b32_e32 v14, v210
	v_mov_b32_e32 v15, v210
	v_mov_b32_e32 v16, v210
	v_mov_b32_e32 v17, v210
	v_mov_b32_e32 v18, 0
	v_mov_b32_e32 v19, v210
	v_mov_b32_e32 v20, v210
	v_mov_b32_e32 v21, v210
	v_mov_b32_e32 v22, v210
	v_mov_b32_e32 v23, v210
	v_mov_b32_e32 v24, v210
	v_mov_b32_e32 v25, v210
	v_mov_b32_e32 v26, v210
	v_mov_b32_e32 v27, v210
	v_mov_b32_e32 v28, v210
	v_mov_b32_e32 v29, v210
	v_mov_b32_e32 v30, v210
	v_mov_b32_e32 v31, v210
	v_mov_b32_e32 v32, v210
	v_mov_b32_e32 v33, v210
	s_mov_b64 s[12:13], 0x40000
	s_mov_b64 s[14:15], 0x20000
	s_mov_b64 s[16:17], 0x30000
	s_mov_b64 s[18:19], 0x50000
	v_cvt_pk_bf16_f32 v158, v82, v83
	v_cvt_pk_bf16_f32 v159, v84, v85
	v_cvt_pk_bf16_f32 v160, v86, v87
	v_cvt_pk_bf16_f32 v161, v88, v89
	v_cvt_pk_bf16_f32 v146, v90, v91
	v_cvt_pk_bf16_f32 v147, v92, v93
	v_cvt_pk_bf16_f32 v148, v94, v95
	v_cvt_pk_bf16_f32 v149, v96, v97
	v_cvt_pk_bf16_f32 v138, v66, v67
	v_cvt_pk_bf16_f32 v139, v68, v69
	v_cvt_pk_bf16_f32 v140, v70, v71
	v_cvt_pk_bf16_f32 v141, v72, v73
	s_mov_b32 s100, 0x10000
	s_mov_b32 s101, 0
	v_lshl_add_u64 v[224:225], v[194:195], 0, s[4:5]
	v_lshl_add_u64 v[228:229], v[196:197], 0, s[4:5]
	v_lshl_add_u64 v[230:231], v[198:199], 0, s[4:5]
	v_lshl_add_u64 v[224:225], v[224:225], 0, s[12:13]
	v_lshl_add_u64 v[228:229], v[228:229], 0, s[14:15]
	v_lshl_add_u64 v[230:231], v[230:231], 0, s[14:15]
.LBB0_798:
	s_mov_b32 s8, s36
	s_mov_b32 s6, s10
	s_mov_b32 s7, s35
	v_add_f32_e32 v98, v82, v83
	v_add_f32_e32 v98, v84, v98
	v_add_f32_e32 v98, v85, v98
	v_add_f32_e32 v98, v86, v98
	v_add_f32_e32 v98, v87, v98
	v_lshl_add_u32 v201, s9, 1, v214
	s_waitcnt lgkmcnt(7)
	v_mfma_f32_32x32x16_bf16 v[114:129], v[186:189], v[154:157], 0
	s_nop 0
	v_add_f32_e32 v82, v88, v98
	v_add_f32_e32 v82, v89, v82
	v_add_f32_e32 v82, v90, v82
	v_add_f32_e32 v82, v91, v82
	s_waitcnt lgkmcnt(6)
	v_mfma_f32_32x32x16_bf16 v[98:113], v[174:177], v[154:157], 0
	v_add_f32_e32 v82, v92, v82
	v_add_f32_e32 v82, v93, v82
	v_add_f32_e32 v82, v94, v82
	v_add_f32_e32 v86, v95, v82
	s_waitcnt lgkmcnt(5)
	v_mfma_f32_32x32x16_bf16 v[114:129], v[190:193], v[150:153], v[114:129]
	ds_read_b64_tr_b16 v[82:83], v201 offset:24576
	ds_read_b64_tr_b16 v[84:85], v201 offset:25088
	v_add_f32_e32 v86, v96, v86
	v_add_f32_e32 v86, v97, v86
	v_add_f32_e32 v86, v66, v86
	v_add_f32_e32 v90, v67, v86
	s_waitcnt lgkmcnt(6)
	v_mfma_f32_32x32x16_bf16 v[98:113], v[178:181], v[150:153], v[98:113]
	ds_read_b64_tr_b16 v[86:87], v201 offset:28672
	ds_read_b64_tr_b16 v[88:89], v201 offset:29184
	v_add_f32_e32 v90, v68, v90
	v_add_f32_e32 v90, v69, v90
	v_add_f32_e32 v90, v70, v90
	v_add_f32_e32 v90, v71, v90
	s_waitcnt lgkmcnt(7)
	v_mfma_f32_32x32x16_bf16 v[114:129], v[182:185], v[142:145], v[114:129]
	ds_read_b64_tr_b16 v[66:67], v201 offset:32768
	ds_read_b64_tr_b16 v[68:69], v201 offset:33280
	v_add_f32_e32 v90, v72, v90
	v_add_f32_e32 v90, v73, v90
	v_add_f32_e32 v90, v74, v90
	v_add_f32_e32 v90, v75, v90
	s_waitcnt lgkmcnt(8)
	v_mfma_f32_32x32x16_bf16 v[98:113], v[166:169], v[142:145], v[98:113]
	ds_read_b64_tr_b16 v[70:71], v201 offset:36864
	ds_read_b64_tr_b16 v[72:73], v201 offset:37376
	v_add_f32_e32 v90, v76, v90
	v_add_f32_e32 v90, v77, v90
	v_add_f32_e32 v90, v78, v90
	v_add_f32_e32 v90, v79, v90
	v_cvt_pk_bf16_f32 v130, v74, v75
	v_cvt_pk_bf16_f32 v131, v76, v77
	s_waitcnt lgkmcnt(9)
	v_mfma_f32_32x32x16_bf16 v[114:129], v[170:173], v[134:137], v[114:129]
	ds_read_b64_tr_b16 v[74:75], v201 offset:25600
	ds_read_b64_tr_b16 v[76:77], v201 offset:26112
	v_add_f32_e32 v90, v80, v90
	v_add_f32_e32 v90, v81, v90
	v_add_f32_e32 v200, 0, v90
	v_cvt_pk_bf16_f32 v132, v78, v79
	v_cvt_pk_bf16_f32 v133, v80, v81
	s_waitcnt lgkmcnt(10)
	v_mfma_f32_32x32x16_bf16 v[98:113], v[162:165], v[134:137], v[98:113]
	s_add_i32 s9, s35, s33
	s_mov_b32 m0, s9
	s_nop 0
	global_load_lds_dwordx4 v[224:225], off
	s_lshl_b32 s9, s36, 1
	s_add_i32 s9, s9, s34
	s_mov_b32 m0, s9
	s_nop 0
	global_load_lds_dwordx4 v[228:229], off
	s_addk_i32 s9, 0x2000
	s_mov_b32 m0, s9
	s_nop 0
	global_load_lds_dwordx4 v[230:231], off
	s_waitcnt lgkmcnt(8)
	v_mfma_f32_32x32x16_bf16 v[34:49], v[158:161], v[82:85], v[34:49]
	v_exp_f32_e32 v114, v114
	v_exp_f32_e32 v115, v115
	ds_read_b64_tr_b16 v[78:79], v201 offset:29696
	ds_read_b64_tr_b16 v[80:81], v201 offset:30208
	s_waitcnt lgkmcnt(8)
	v_mfma_f32_32x32x16_bf16 v[50:65], v[158:161], v[86:89], v[50:65]
	v_exp_f32_e32 v116, v116
	v_exp_f32_e32 v117, v117
	v_lshl_add_u64 v[224:225], v[224:225], 0, s[100:101]
	ds_read_b64_tr_b16 v[82:83], v201 offset:33792
	ds_read_b64_tr_b16 v[84:85], v201 offset:34304
	s_waitcnt lgkmcnt(8)
	v_mfma_f32_32x32x16_bf16 v[2:17], v[158:161], v[66:69], v[2:17]
	v_exp_f32_e32 v118, v118
	v_exp_f32_e32 v119, v119
	v_lshl_add_u64 v[228:229], v[228:229], 0, s[100:101]
	ds_read_b64_tr_b16 v[86:87], v201 offset:37888
	ds_read_b64_tr_b16 v[88:89], v201 offset:38400
	s_waitcnt lgkmcnt(8)
	v_mfma_f32_32x32x16_bf16 v[18:33], v[158:161], v[70:73], v[18:33]
	v_exp_f32_e32 v120, v120
	v_exp_f32_e32 v121, v121
	v_lshl_add_u64 v[230:231], v[230:231], 0, s[100:101]
	ds_read_b64_tr_b16 v[70:71], v201 offset:26624
	ds_read_b64_tr_b16 v[72:73], v201 offset:27136
	v_add_u32_e32 v94, s8, v212
	v_add_u32_e32 v220, s8, v217
	v_add_u32_e32 v221, s8, v218
	v_add_u32_e32 v222, s8, v219
	ds_read_b128 v[90:93], v94
	ds_read_b128 v[66:69], v94 offset:4096
	s_waitcnt lgkmcnt(10)
	v_mfma_f32_32x32x16_bf16 v[34:49], v[146:149], v[74:77], v[34:49]
	v_exp_f32_e32 v122, v122
	v_exp_f32_e32 v123, v123
	v_cvt_pk_bf16_f32 v158, v114, v115
	ds_read_b64_tr_b16 v[74:75], v201 offset:30720
	ds_read_b64_tr_b16 v[76:77], v201 offset:31232
	s_waitcnt lgkmcnt(10)
	v_mfma_f32_32x32x16_bf16 v[50:65], v[146:149], v[78:81], v[50:65]
	v_exp_f32_e32 v124, v124
	v_exp_f32_e32 v125, v125
	v_cvt_pk_bf16_f32 v159, v116, v117
	ds_read_b64_tr_b16 v[78:79], v201 offset:34816
	ds_read_b64_tr_b16 v[80:81], v201 offset:35328
	s_waitcnt lgkmcnt(10)
	v_mfma_f32_32x32x16_bf16 v[2:17], v[146:149], v[82:85], v[2:17]
	v_exp_f32_e32 v126, v126
	v_exp_f32_e32 v127, v127
	v_cvt_pk_bf16_f32 v160, v118, v119
	ds_read_b64_tr_b16 v[82:83], v201 offset:38912
	ds_read_b64_tr_b16 v[84:85], v201 offset:39424
	ds_read_b128 v[168:171], v220
	ds_read_b128 v[172:175], v220 offset:4096
	s_waitcnt lgkmcnt(12)
	v_mfma_f32_32x32x16_bf16 v[18:33], v[146:149], v[86:89], v[18:33]
	v_exp_f32_e32 v128, v128
	v_exp_f32_e32 v129, v129
	v_cvt_pk_bf16_f32 v161, v120, v121
	ds_read_b64_tr_b16 v[86:87], v201 offset:27648
	ds_read_b64_tr_b16 v[88:89], v201 offset:28160
	s_waitcnt lgkmcnt(12)
	v_mfma_f32_32x32x16_bf16 v[34:49], v[138:141], v[70:73], v[34:49]
	v_exp_f32_e32 v98, v98
	v_exp_f32_e32 v99, v99
	v_cvt_pk_bf16_f32 v146, v122, v123
	ds_read_b64_tr_b16 v[70:71], v201 offset:31744
	ds_read_b64_tr_b16 v[72:73], v201 offset:32256
	s_waitcnt lgkmcnt(10)
	v_mfma_f32_32x32x16_bf16 v[50:65], v[138:141], v[74:77], v[50:65]
	v_exp_f32_e32 v100, v100
	v_exp_f32_e32 v101, v101
	v_cvt_pk_bf16_f32 v147, v124, v125
	ds_read_b64_tr_b16 v[74:75], v201 offset:35840
	ds_read_b64_tr_b16 v[76:77], v201 offset:36352
	ds_read_b128 v[176:179], v221
	ds_read_b128 v[180:183], v221 offset:4096
	s_waitcnt lgkmcnt(12)
	v_mfma_f32_32x32x16_bf16 v[2:17], v[138:141], v[78:81], v[2:17]
	v_exp_f32_e32 v102, v102
	v_exp_f32_e32 v103, v103
	v_cvt_pk_bf16_f32 v148, v126, v127
	ds_read_b64_tr_b16 v[78:79], v201 offset:39936
	ds_read_b64_tr_b16 v[80:81], v201 offset:40448
	s_waitcnt lgkmcnt(12)
	v_mfma_f32_32x32x16_bf16 v[18:33], v[138:141], v[82:85], v[18:33]
	v_exp_f32_e32 v104, v104
	v_exp_f32_e32 v105, v105
	v_cvt_pk_bf16_f32 v149, v128, v129
	s_waitcnt lgkmcnt(8)
	v_mfma_f32_32x32x16_bf16 v[34:49], v[130:133], v[86:89], v[34:49]
	v_exp_f32_e32 v106, v106
	v_exp_f32_e32 v107, v107
	v_cvt_pk_bf16_f32 v138, v98, v99
	ds_read_b128 v[184:187], v222
	ds_read_b128 v[188:191], v222 offset:4096
	s_waitcnt lgkmcnt(8)
	v_mfma_f32_32x32x16_bf16 v[50:65], v[130:133], v[70:73], v[50:65]
	v_exp_f32_e32 v108, v108
	v_exp_f32_e32 v109, v109
	v_cvt_pk_bf16_f32 v139, v100, v101
	s_waitcnt lgkmcnt(6)
	v_mfma_f32_32x32x16_bf16 v[2:17], v[130:133], v[74:77], v[2:17]
	v_exp_f32_e32 v110, v110
	v_exp_f32_e32 v111, v111
	v_cvt_pk_bf16_f32 v140, v102, v103
	s_waitcnt lgkmcnt(2)
	v_mfma_f32_32x32x16_bf16 v[18:33], v[130:133], v[78:81], v[18:33]
	v_exp_f32_e32 v112, v112
	v_exp_f32_e32 v113, v113
	v_cvt_pk_bf16_f32 v141, v104, v105
	s_waitcnt vmcnt(3) lgkmcnt(0)
	s_barrier
	s_add_i32 s9, s36, 0x2000
	s_cmpk_lg_i32 s36, 0x4000
	s_cselect_b32 s35, s9, 0
	v_mfma_f32_32x32x16_bf16 v[82:97], v[90:93], v[154:157], 0
	v_add_f32_e32 v70, v114, v115
	v_add_f32_e32 v70, v116, v70
	v_add_f32_e32 v70, v117, v70
	v_add_f32_e32 v70, v118, v70
	v_add_f32_e32 v70, v119, v70
	v_lshl_add_u32 v201, s7, 1, v214
	s_nop 0
	v_add_f32_e32 v70, v120, v70
	v_add_f32_e32 v70, v121, v70
	v_add_f32_e32 v70, v122, v70
	v_add_f32_e32 v114, v123, v70
	v_mfma_f32_32x32x16_bf16 v[66:81], v[66:69], v[154:157], 0
	v_mfma_f32_32x32x16_bf16 v[82:97], v[168:171], v[150:153], v[82:97]
	v_add_f32_e32 v114, v124, v114
	v_add_f32_e32 v114, v125, v114
	v_add_f32_e32 v114, v126, v114
	v_add_f32_e32 v118, v127, v114
	ds_read_b64_tr_b16 v[114:115], v201 offset:24576
	ds_read_b64_tr_b16 v[116:117], v201 offset:25088
	v_mfma_f32_32x32x16_bf16 v[66:81], v[172:175], v[150:153], v[66:81]
	v_add_f32_e32 v118, v128, v118
	v_add_f32_e32 v118, v129, v118
	v_add_f32_e32 v118, v98, v118
	v_add_f32_e32 v122, v99, v118
	ds_read_b64_tr_b16 v[118:119], v201 offset:28672
	ds_read_b64_tr_b16 v[120:121], v201 offset:29184
	v_mfma_f32_32x32x16_bf16 v[82:97], v[176:179], v[142:145], v[82:97]
	v_add_f32_e32 v122, v100, v122
	v_add_f32_e32 v122, v101, v122
	v_add_f32_e32 v122, v102, v122
	v_add_f32_e32 v122, v103, v122
	ds_read_b64_tr_b16 v[98:99], v201 offset:32768
	ds_read_b64_tr_b16 v[100:101], v201 offset:33280
	v_mfma_f32_32x32x16_bf16 v[66:81], v[180:183], v[142:145], v[66:81]
	v_add_f32_e32 v122, v104, v122
	v_add_f32_e32 v122, v105, v122
	v_add_f32_e32 v122, v106, v122
	v_add_f32_e32 v122, v107, v122
	ds_read_b64_tr_b16 v[102:103], v201 offset:36864
	ds_read_b64_tr_b16 v[104:105], v201 offset:37376
	s_waitcnt lgkmcnt(9)
; #define WAIT_BAR(N) asm volatile("s_waitcnt vmcnt(" #N ") lgkmcnt(0)\n\ts_barrier":::"memory")
;   #define RESC() do{ if(resc){ asm volatile("s_waitcnt lgkmcnt(0)":::"memory"); \
;       _Pragma("unroll") for(int d_=0;d_<2;++d_) _Pragma("unroll") for(int r=0;r<16;++r)o[d_][r]*=wsf[crow(r,hi)]; } }while(0)
;   #define ROT() do{sl_prev=sl_cur;sl_cur=sl_next;sl_next=(sl_next==(NSLOT-1)*SLOTB)?0:sl_next+SLOTB;}while(0)
;   #define RESC() do{ if(resc){ asm volatile("s_waitcnt lgkmcnt(0)":::"memory"); \
;       _Pragma("unroll") for(int d_=0;d_<4;++d_) _Pragma("unroll") for(int r=0;r<16;++r)o[d_][r]*=wsf[crow(r,hi)]; } }while(0)
;   #define ROT() do{sl_prev=sl_cur;sl_cur=sl_next;sl_next=(sl_next==(NSLOT-1)*SLOTB)?0:sl_next+SLOTB;}while(0)
; template<int THRL,bool NOMAX=false> __device__ __forceinline__ void attn_unit_v128(const bf16*Qu,int qp,const bf16*__restrict__ Kh,int kp,const bf16*__restrict__ Vh,int vp,bf16*Ou,int op,int NT,char*shm,int tid_in){
;     ...
;   for(;t+5<NT;t+=2){
;     STEP(pB0,pB1,pA0,pA1,t,true,true,true);     WAIT_BAR(3); RESC(); ROT();
;     STEP(pA0,pA1,pB0,pB1,t+1,true,true,true);   WAIT_BAR(3); RESC(); ROT();
	v_mfma_f32_32x32x16_bf16 v[82:97], v[184:187], v[134:137], v[82:97]
	v_add_f32_e32 v122, v108, v122
	v_add_f32_e32 v122, v109, v122
	v_add_f32_e32 v122, v110, v122
	v_add_f32_e32 v122, v111, v122
	v_cvt_pk_bf16_f32 v130, v106, v107
	v_cvt_pk_bf16_f32 v131, v108, v109
	ds_read_b64_tr_b16 v[106:107], v201 offset:25600
	ds_read_b64_tr_b16 v[108:109], v201 offset:26112
	s_waitcnt lgkmcnt(10)
	v_mfma_f32_32x32x16_bf16 v[66:81], v[188:191], v[134:137], v[66:81]
	v_add_f32_e32 v122, v112, v122
	v_add_f32_e32 v122, v113, v122
	v_add_f32_e32 v122, 0, v122
	v_cvt_pk_bf16_f32 v132, v110, v111
	v_cvt_pk_bf16_f32 v133, v112, v113
	s_add_i32 s7, s36, s33
	s_mov_b32 m0, s7
	s_nop 0
	global_load_lds_dwordx4 v[224:225], off
	s_lshl_b32 s7, s35, 1
	s_add_i32 s7, s7, s34
	s_mov_b32 m0, s7
	s_nop 0
	global_load_lds_dwordx4 v[228:229], off
	s_addk_i32 s7, 0x2000
	s_mov_b32 m0, s7
	s_nop 0
	global_load_lds_dwordx4 v[230:231], off
	s_waitcnt lgkmcnt(8)
	v_mfma_f32_32x32x16_bf16 v[34:49], v[158:161], v[114:117], v[34:49]
	v_exp_f32_e32 v82, v82
	v_exp_f32_e32 v83, v83
	ds_read_b64_tr_b16 v[110:111], v201 offset:29696
	ds_read_b64_tr_b16 v[112:113], v201 offset:30208
	s_waitcnt lgkmcnt(8)
	v_mfma_f32_32x32x16_bf16 v[50:65], v[158:161], v[118:121], v[50:65]
	v_exp_f32_e32 v84, v84
	v_exp_f32_e32 v85, v85
	v_lshl_add_u64 v[224:225], v[224:225], 0, s[100:101]
	ds_read_b64_tr_b16 v[114:115], v201 offset:33792
	ds_read_b64_tr_b16 v[116:117], v201 offset:34304
	s_waitcnt lgkmcnt(8)
	v_mfma_f32_32x32x16_bf16 v[2:17], v[158:161], v[98:101], v[2:17]
	v_exp_f32_e32 v86, v86
	v_exp_f32_e32 v87, v87
	v_lshl_add_u64 v[228:229], v[228:229], 0, s[100:101]
	ds_read_b64_tr_b16 v[98:99], v201 offset:37888
	ds_read_b64_tr_b16 v[100:101], v201 offset:38400
	s_waitcnt lgkmcnt(8)
	v_mfma_f32_32x32x16_bf16 v[18:33], v[158:161], v[102:105], v[18:33]
	v_exp_f32_e32 v88, v88
	v_exp_f32_e32 v89, v89
	v_lshl_add_u64 v[230:231], v[230:231], 0, s[100:101]
	ds_read_b64_tr_b16 v[102:103], v201 offset:26624
	ds_read_b64_tr_b16 v[104:105], v201 offset:27136
	v_add_u32_e32 v118, s35, v212
	v_add_u32_e32 v220, s35, v217
	v_add_u32_e32 v221, s35, v218
	v_add_u32_e32 v222, s35, v219
	ds_read_b128 v[186:189], v118
	ds_read_b128 v[174:177], v118 offset:4096
	s_waitcnt lgkmcnt(10)
	v_mfma_f32_32x32x16_bf16 v[34:49], v[146:149], v[106:109], v[34:49]
	v_exp_f32_e32 v90, v90
	v_exp_f32_e32 v91, v91
	v_cvt_pk_bf16_f32 v158, v82, v83
	ds_read_b64_tr_b16 v[106:107], v201 offset:30720
	ds_read_b64_tr_b16 v[108:109], v201 offset:31232
	s_waitcnt lgkmcnt(10)
	v_mfma_f32_32x32x16_bf16 v[50:65], v[146:149], v[110:113], v[50:65]
	v_exp_f32_e32 v92, v92
	v_exp_f32_e32 v93, v93
	v_cvt_pk_bf16_f32 v159, v84, v85
	ds_read_b64_tr_b16 v[110:111], v201 offset:34816
	ds_read_b64_tr_b16 v[112:113], v201 offset:35328
	s_waitcnt lgkmcnt(10)
	v_mfma_f32_32x32x16_bf16 v[2:17], v[146:149], v[114:117], v[2:17]
	v_exp_f32_e32 v94, v94
	v_exp_f32_e32 v95, v95
	v_cvt_pk_bf16_f32 v160, v86, v87
	ds_read_b64_tr_b16 v[114:115], v201 offset:38912
	ds_read_b64_tr_b16 v[116:117], v201 offset:39424
	ds_read_b128 v[190:193], v220
	ds_read_b128 v[178:181], v220 offset:4096
	s_waitcnt lgkmcnt(12)
	v_mfma_f32_32x32x16_bf16 v[18:33], v[146:149], v[98:101], v[18:33]
	v_exp_f32_e32 v96, v96
	v_exp_f32_e32 v97, v97
	v_cvt_pk_bf16_f32 v161, v88, v89
	ds_read_b64_tr_b16 v[98:99], v201 offset:27648
	ds_read_b64_tr_b16 v[100:101], v201 offset:28160
	s_waitcnt lgkmcnt(12)
	v_mfma_f32_32x32x16_bf16 v[34:49], v[138:141], v[102:105], v[34:49]
	v_exp_f32_e32 v66, v66
	v_exp_f32_e32 v67, v67
	v_cvt_pk_bf16_f32 v146, v90, v91
	ds_read_b64_tr_b16 v[102:103], v201 offset:31744
	ds_read_b64_tr_b16 v[104:105], v201 offset:32256
	s_waitcnt lgkmcnt(10)
	v_mfma_f32_32x32x16_bf16 v[50:65], v[138:141], v[106:109], v[50:65]
	v_exp_f32_e32 v68, v68
	v_exp_f32_e32 v69, v69
	v_cvt_pk_bf16_f32 v147, v92, v93
	ds_read_b64_tr_b16 v[106:107], v201 offset:35840
	ds_read_b64_tr_b16 v[108:109], v201 offset:36352
	ds_read_b128 v[182:185], v221
	ds_read_b128 v[166:169], v221 offset:4096
	s_waitcnt lgkmcnt(12)
	v_mfma_f32_32x32x16_bf16 v[2:17], v[138:141], v[110:113], v[2:17]
	v_exp_f32_e32 v70, v70
	v_exp_f32_e32 v71, v71
	v_cvt_pk_bf16_f32 v148, v94, v95
	ds_read_b64_tr_b16 v[110:111], v201 offset:39936
	ds_read_b64_tr_b16 v[112:113], v201 offset:40448
	s_waitcnt lgkmcnt(12)
	v_mfma_f32_32x32x16_bf16 v[18:33], v[138:141], v[114:117], v[18:33]
	v_exp_f32_e32 v72, v72
	v_exp_f32_e32 v73, v73
	v_cvt_pk_bf16_f32 v149, v96, v97
	s_waitcnt lgkmcnt(8)
	v_mfma_f32_32x32x16_bf16 v[34:49], v[130:133], v[98:101], v[34:49]
	v_exp_f32_e32 v74, v74
	v_exp_f32_e32 v75, v75
	v_cvt_pk_bf16_f32 v138, v66, v67
	ds_read_b128 v[170:173], v222
	ds_read_b128 v[162:165], v222 offset:4096
	s_waitcnt lgkmcnt(8)
	v_mfma_f32_32x32x16_bf16 v[50:65], v[130:133], v[102:105], v[50:65]
	v_exp_f32_e32 v76, v76
	v_exp_f32_e32 v77, v77
	v_cvt_pk_bf16_f32 v139, v68, v69
	s_waitcnt lgkmcnt(6)
	v_mfma_f32_32x32x16_bf16 v[2:17], v[130:133], v[106:109], v[2:17]
	v_exp_f32_e32 v78, v78
	v_exp_f32_e32 v79, v79
	v_cvt_pk_bf16_f32 v140, v70, v71
	s_waitcnt lgkmcnt(2)
	v_mfma_f32_32x32x16_bf16 v[18:33], v[130:133], v[110:113], v[18:33]
	v_exp_f32_e32 v80, v80
	v_exp_f32_e32 v81, v81
	v_cvt_pk_bf16_f32 v141, v72, v73
	s_add_i32 s7, s35, 0x2000
	s_cmpk_lg_i32 s35, 0x4000
	s_mov_b32 s9, s36
	s_cselect_b32 s36, s7, 0
	s_add_i32 s10, s6, 2
	s_waitcnt vmcnt(3) lgkmcnt(0)
	s_barrier
	s_add_u32 s4, s4, 0x20000
	v_add_f32_e32 v98, v210, v200
	s_addc_u32 s5, s5, 0
	s_cmp_ge_u32 s10, s75
	v_add_f32_e32 v210, v98, v122
	s_cbranch_scc0 .LBB0_798
	s_add_i32 s86, s6, -3
	s_add_i32 s4, s86, 1
	s_cmp_ge_u32 s4, s75
	s_mov_b64 s[4:5], -1
	s_cbranch_scc0 .LBB0_802
	s_branch .LBB0_801
